# prep phase: rope operand and rope-table loads also issued with the first window batch (two more round trips removed per row)
# speedup vs baseline: 1.0028x; 1.0028x over previous
; __device__ __forceinline__ float bf_lo(unsigned u) { return __uint_as_float(u << 16); }
; __device__ __forceinline__ float bf_hi(unsigned u) { return __uint_as_float(u & 0xffff0000u); }
; __device__ void prep_phase(PK p) {
;     ...
;             const int wdw = 2 << (lane >> 4), hw = wdw >> 1; const int lo = max(t - hw, 0), hi = min(t + hw, n);
;             float s0 = 0.f, s1 = 0.f, s2 = 0.f, s3 = 0.f;
; #pragma unroll
;             for (int i = 0; i < 16; ++i) {
;                 const int off = i - 8, tt = t + off; const bool ok = (off >= -hw) && (off < hw) && (tt >= 0) && (tt < n);
;                 const u32x2 v = *(const u32x2*)(PJ + (size_t)(sbase + (ok ? tt : t)) * PJW + 4 * lane); const float wg = ok ? 1.0f : 0.0f;
;                 s0 += wg * bf_lo(v.x); s1 += wg * bf_hi(v.x); s2 += wg * bf_lo(v.y); s3 += wg * bf_hi(v.y); }
;     ...
;         if (lane < 34) {
;             const bool iskr = lane >= 32; const int a = lane & 1;
;             bf16_t* ep = iskr ? prow + C_MKR + a * 16 : prow + ((lane >> 4) ? C_DK : C_DQ) + ((lane >> 1) & 7) * 32 + a * 16;
;             const u32x4 e0 = *(const u32x4*)ep, e1 = *(const u32x4*)(ep + 8);
;             float x1[8], x2[8];
;             x1[0] = bf_lo(e0.x); x1[1] = bf_hi(e0.x); x1[2] = bf_lo(e0.y); x1[3] = bf_hi(e0.y); x1[4] = bf_lo(e0.z); x1[5] = bf_hi(e0.z); x1[6] = bf_lo(e0.w); x1[7] = bf_hi(e0.w);
;             x2[0] = bf_lo(e1.x); x2[1] = bf_hi(e1.x); x2[2] = bf_lo(e1.y); x2[3] = bf_hi(e1.y); x2[4] = bf_lo(e1.z); x2[5] = bf_hi(e1.z); x2[6] = bf_lo(e1.w); x2[7] = bf_hi(e1.w);
;             if (lat) { const int pos = a ? (t & 63) : (t >> 6);
.LBB0_489:
	v_cmp_gt_i32_e64 s[18:19], s95, v14
	v_and_b32_e32 v7, 0x1fff, v14
	v_and_b32_e32 v2, 0xff, v14
	v_mov_b32_e32 v3, 0x2000
	s_waitcnt lgkmcnt(0)
	v_mov_b32_e32 v4, 0x100
	v_cndmask_b32_e64 v37, v2, v7, s[18:19]
	v_cndmask_b32_e64 v15, v4, v3, s[18:19]
	v_add_u32_e32 v2, -8, v37
	v_cmp_lt_u32_e32 vcc, v2, v15
	s_and_b64 vcc, s[14:15], vcc
	v_add_u32_e32 v4, -7, v37
	v_cndmask_b32_e32 v2, v37, v2, vcc
	v_cndmask_b32_e64 v6, 0, 1.0, vcc
	v_cmp_lt_u32_e32 vcc, v4, v15
	s_and_b64 vcc, s[14:15], vcc
	v_sub_u32_e32 v2, v2, v37
	v_cndmask_b32_e32 v4, v37, v4, vcc
	v_sub_u32_e32 v4, v4, v37
	v_add_u32_e32 v2, v14, v2
	v_add_u32_e32 v4, v14, v4
	v_mad_i64_i32 v[2:3], s[0:1], v2, s56, v[16:17]
	v_mad_i64_i32 v[4:5], s[0:1], v4, s56, v[16:17]
	global_load_dwordx2 v[2:3], v[2:3], off
	v_cndmask_b32_e64 v10, 0, 1.0, vcc
	global_load_dwordx2 v[8:9], v[4:5], off
	v_add_u32_e32 v4, -6, v37
	v_cmp_lt_u32_e32 vcc, v4, v15
	s_and_b64 vcc, s[14:15], vcc
	v_readlane_b32 s2, v254, 56
	v_cndmask_b32_e32 v4, v37, v4, vcc
	v_sub_u32_e32 v4, v4, v37
	v_add_u32_e32 v4, v14, v4
	v_mad_i64_i32 v[4:5], s[0:1], v4, s56, v[16:17]
	global_load_dwordx2 v[12:13], v[4:5], off
	v_add_u32_e32 v4, -5, v37
	v_cndmask_b32_e64 v34, 0, 1.0, vcc
	v_cmp_lt_u32_e32 vcc, v4, v15
	s_and_b64 vcc, s[14:15], vcc
	v_readlane_b32 s3, v254, 57
	v_cndmask_b32_e32 v4, v37, v4, vcc
	v_sub_u32_e32 v4, v4, v37
	v_add_u32_e32 v4, v14, v4
	v_mad_i64_i32 v[4:5], s[0:1], v4, s56, v[16:17]
	global_load_dwordx2 v[38:39], v[4:5], off
	v_add_u32_e32 v4, -4, v37
	v_cndmask_b32_e64 v36, 0, 1.0, vcc
	v_cmp_lt_u32_e32 vcc, v4, v15
	s_and_b64 vcc, s[8:9], vcc
	v_sub_u32_e32 v19, v37, v1
	v_cndmask_b32_e32 v4, v37, v4, vcc
	v_sub_u32_e32 v4, v4, v37
	v_add_u32_e32 v4, v14, v4
	v_mad_i64_i32 v[4:5], s[0:1], v4, s56, v[16:17]
	global_load_dwordx2 v[40:41], v[4:5], off
	v_add_u32_e32 v4, -3, v37
	v_cndmask_b32_e64 v42, 0, 1.0, vcc
	v_cmp_lt_u32_e32 vcc, v4, v15
	s_and_b64 vcc, s[8:9], vcc
	v_add_u32_e32 v33, v37, v1
	v_cndmask_b32_e32 v4, v37, v4, vcc
	v_sub_u32_e32 v4, v4, v37
	v_add_u32_e32 v4, v14, v4
	v_mad_i64_i32 v[4:5], s[0:1], v4, s56, v[16:17]
	global_load_dwordx2 v[44:45], v[4:5], off
	v_add_u32_e32 v4, -2, v37
	v_cndmask_b32_e64 v46, 0, 1.0, vcc
	v_cmp_lt_u32_e32 vcc, v4, v15
	s_and_b64 vcc, s[16:17], vcc
	v_max_i32_e32 v19, 0, v19
	v_cndmask_b32_e32 v4, v37, v4, vcc
	v_sub_u32_e32 v4, v4, v37
	v_add_u32_e32 v4, v14, v4
	v_mad_i64_i32 v[4:5], s[0:1], v4, s56, v[16:17]
	global_load_dwordx2 v[48:49], v[4:5], off
	v_cndmask_b32_e64 v50, 0, 1.0, vcc
	s_mov_b32 s98, 0x78de000
	s_mov_b32 s99, 0
	v_lshl_add_u64 v[80:81], s[2:3], 0, v[24:25]
	v_lshl_add_u64 v[84:85], s[2:3], 0, v[30:31]
	v_lshl_add_u64 v[80:81], v[80:81], 0, s[98:99]
	global_load_dword v86, v[84:85], off
	global_load_dwordx2 v[82:83], v[80:81], off offset:3584
	v_lshl_add_u64 v[112:113], s[2:3], 0, v[28:29]
	v_lshl_add_u64 v[114:115], s[2:3], 0, v[26:27]
	v_and_b32_e32 v116, 63, v14
	v_lshrrev_b32_e32 v117, 6, v7
	v_cndmask_b32_e64 v113, v115, v113, s[8:9]
	v_cndmask_b32_e64 v112, v114, v112, s[8:9]
	v_mov_b32_e32 v114, v32
	v_mov_b32_e32 v115, 0
	v_cndmask_b32_e64 v116, v116, v117, s[12:13]
	v_lshl_add_u64 v[112:113], v[112:113], 0, v[114:115]
	v_lshlrev_b32_e32 v116, 6, v116
	global_load_dwordx4 v[88:91], v[112:113], off
	global_load_dwordx4 v[92:95], v[112:113], off offset:16
	global_load_dwordx4 v[108:111], v116, s[26:27] offset:48
	global_load_dwordx4 v[104:107], v116, s[26:27] offset:32
	global_load_dwordx4 v[100:103], v116, s[26:27] offset:16
	global_load_dwordx4 v[96:99], v116, s[26:27]
	s_waitcnt vmcnt(8)
	v_lshlrev_b32_e32 v4, 16, v2
	v_and_b32_e32 v5, 0xffff0000, v2
	v_lshlrev_b32_e32 v2, 16, v3
	v_and_b32_e32 v3, 0xffff0000, v3
	v_lshlrev_b32_e32 v52, 16, v8
	v_and_b32_e32 v53, 0xffff0000, v8
	v_pk_fma_f32 v[2:3], v[6:7], v[2:3], 0 op_sel_hi:[0,1,0]
	v_lshlrev_b32_e32 v8, 16, v9
	v_and_b32_e32 v9, 0xffff0000, v9
	v_pk_fma_f32 v[4:5], v[6:7], v[4:5], 0 op_sel_hi:[0,1,0]
	v_pk_fma_f32 v[2:3], v[10:11], v[8:9], v[2:3] op_sel_hi:[0,1,1]
	v_add_u32_e32 v6, -1, v37
	v_lshlrev_b32_e32 v8, 16, v13
	v_and_b32_e32 v9, 0xffff0000, v13
	v_pk_fma_f32 v[2:3], v[34:35], v[8:9], v[2:3] op_sel_hi:[0,1,1]
	v_cmp_lt_u32_e32 vcc, v6, v15
	v_pk_fma_f32 v[4:5], v[10:11], v[52:53], v[4:5] op_sel_hi:[0,1,1]
	v_lshlrev_b32_e32 v52, 16, v12
	v_cndmask_b32_e32 v6, v37, v6, vcc
	v_and_b32_e32 v53, 0xffff0000, v12
	v_sub_u32_e32 v6, v6, v37
	v_pk_fma_f32 v[4:5], v[34:35], v[52:53], v[4:5] op_sel_hi:[0,1,1]
	v_add_u32_e32 v6, v14, v6
	v_lshlrev_b32_e32 v8, 16, v39
	v_and_b32_e32 v9, 0xffff0000, v39
	v_pk_fma_f32 v[2:3], v[36:37], v[8:9], v[2:3] op_sel_hi:[0,1,1]
	v_lshlrev_b32_e32 v52, 16, v38
	v_and_b32_e32 v53, 0xffff0000, v38
	v_pk_fma_f32 v[4:5], v[36:37], v[52:53], v[4:5] op_sel_hi:[0,1,1]
	v_lshl_add_u64 v[10:11], s[2:3], 0, v[24:25]
	v_lshlrev_b32_e32 v8, 16, v41
	v_and_b32_e32 v9, 0xffff0000, v41
	v_pk_fma_f32 v[2:3], v[42:43], v[8:9], v[2:3] op_sel_hi:[0,1,1]
	v_lshlrev_b32_e32 v52, 16, v40
	v_and_b32_e32 v53, 0xffff0000, v40
	v_add_u32_e32 v40, 1, v37
	v_pk_fma_f32 v[4:5], v[42:43], v[52:53], v[4:5] op_sel_hi:[0,1,1]
	v_lshlrev_b32_e32 v8, 16, v45
	v_and_b32_e32 v9, 0xffff0000, v45
	v_pk_fma_f32 v[2:3], v[46:47], v[8:9], v[2:3] op_sel_hi:[0,1,1]
	v_lshlrev_b32_e32 v52, 16, v44
	v_and_b32_e32 v53, 0xffff0000, v44
	v_pk_fma_f32 v[4:5], v[46:47], v[52:53], v[4:5] op_sel_hi:[0,1,1]
	v_lshlrev_b32_e32 v8, 16, v49
	v_and_b32_e32 v9, 0xffff0000, v49
	v_pk_fma_f32 v[2:3], v[50:51], v[8:9], v[2:3] op_sel_hi:[0,1,1]
	v_mad_i64_i32 v[8:9], s[0:1], v6, s56, v[16:17]
	v_cndmask_b32_e64 v6, 0, 1.0, vcc
	v_cmp_lt_u32_e32 vcc, v37, v15
	s_mov_b32 s0, 0x78de000
	v_add_co_u32_e64 v10, s[20:21], s0, v10
	v_cndmask_b32_e64 v36, 0, 1.0, vcc
	v_cmp_lt_u32_e32 vcc, v40, v15
	s_and_b64 vcc, s[16:17], vcc
	v_addc_co_u32_e64 v11, s[20:21], 0, v11, s[20:21]
	v_cndmask_b32_e32 v40, v37, v40, vcc
	v_sub_u32_e32 v40, v40, v37
	v_add_u32_e32 v40, v14, v40
	v_mad_i64_i32 v[40:41], s[0:1], v40, s56, v[16:17]
	global_load_dwordx2 v[8:9], v[8:9], off
	v_lshlrev_b32_e32 v52, 16, v48
	global_load_dwordx2 v[12:13], v[10:11], off
	global_load_dwordx2 v[42:43], v[40:41], off
	v_add_u32_e32 v41, 2, v37
	v_cndmask_b32_e64 v40, 0, 1.0, vcc
	v_cmp_lt_u32_e32 vcc, v41, v15
	s_and_b64 vcc, s[8:9], vcc
	v_and_b32_e32 v53, 0xffff0000, v48
	v_cndmask_b32_e32 v41, v37, v41, vcc
	v_sub_u32_e32 v41, v41, v37
	v_add_u32_e32 v41, v14, v41
	v_mad_i64_i32 v[44:45], s[0:1], v41, s56, v[16:17]
	v_add_u32_e32 v41, 3, v37
	global_load_dwordx2 v[46:47], v[44:45], off
	v_cndmask_b32_e64 v44, 0, 1.0, vcc
	v_cmp_lt_u32_e32 vcc, v41, v15
	s_and_b64 vcc, s[8:9], vcc
	v_pk_fma_f32 v[4:5], v[50:51], v[52:53], v[4:5] op_sel_hi:[0,1,1]
	v_cndmask_b32_e32 v41, v37, v41, vcc
	v_sub_u32_e32 v41, v41, v37
	v_add_u32_e32 v41, v14, v41
	v_mad_i64_i32 v[50:51], s[0:1], v41, s56, v[16:17]
	v_add_u32_e32 v41, 4, v37
	global_load_dwordx2 v[52:53], v[50:51], off
	v_cndmask_b32_e64 v50, 0, 1.0, vcc
	v_cmp_lt_u32_e32 vcc, v41, v15
	s_and_b64 vcc, s[14:15], vcc
	s_waitcnt vmcnt(0)
; __device__ __forceinline__ unsigned cvt_pk_bf16(float lo, float hi) { const f32x2_ v = {lo, hi}; return __builtin_bit_cast(unsigned, __builtin_convertvector(v, bf16x2_)); }
; __device__ __forceinline__ float bf_lo(unsigned u) { return __uint_as_float(u << 16); }
; __device__ __forceinline__ float bf_hi(unsigned u) { return __uint_as_float(u & 0xffff0000u); }
; __device__ void prep_phase(PK p) {
;     ...
;             for (int i = 0; i < 16; ++i) {
;                 const int off = i - 8, tt = t + off; const bool ok = (off >= -hw) && (off < hw) && (tt >= 0) && (tt < n);
;                 const u32x2 v = *(const u32x2*)(PJ + (size_t)(sbase + (ok ? tt : t)) * PJW + 4 * lane); const float wg = ok ? 1.0f : 0.0f;
;                 s0 += wg * bf_lo(v.x); s1 += wg * bf_hi(v.x); s2 += wg * bf_lo(v.y); s3 += wg * bf_hi(v.y); }
;             const float ic = 1.0f / (float)(hi - lo); const u32x2 sv = *(const u32x2*)(prow + 4 * lane);
;             u32x2 w; w.x = cvt_pk_bf16(s0 * ic - bf_lo(sv.x), s1 * ic - bf_hi(sv.x)); w.y = cvt_pk_bf16(s2 * ic - bf_lo(sv.y), s3 * ic - bf_hi(sv.y));
;             *(u32x2*)(YB + (size_t)row * 1024 + 4 * lane) = w;
;         }
;         {
;             const u32x2 q = *(const u32x2*)(prow + C_MQ + 4 * lane); const unsigned kv = *(const unsigned*)(prow + C_MKV + 2 * lane);
;             float sq = bf_lo(q.x) * bf_lo(q.x) + bf_hi(q.x) * bf_hi(q.x) + bf_lo(q.y) * bf_lo(q.y) + bf_hi(q.y) * bf_hi(q.y);
;             float sk = bf_lo(kv) * bf_lo(kv) + bf_hi(kv) * bf_hi(kv);
;             sq = wave_sum(sq); sk = wave_sum(sk);
	v_lshlrev_b32_e32 v34, 16, v8
	v_cndmask_b32_e32 v41, v37, v41, vcc
	v_sub_u32_e32 v41, v41, v37
	v_add_u32_e32 v41, v14, v41
	v_mad_i64_i32 v[54:55], s[0:1], v41, s56, v[16:17]
	v_add_u32_e32 v41, 5, v37
	global_load_dwordx2 v[56:57], v[54:55], off
	v_cndmask_b32_e64 v54, 0, 1.0, vcc
	v_cmp_lt_u32_e32 vcc, v41, v15
	s_and_b64 vcc, s[14:15], vcc
	v_and_b32_e32 v35, 0xffff0000, v8
	v_cndmask_b32_e32 v41, v37, v41, vcc
	v_sub_u32_e32 v41, v41, v37
	v_add_u32_e32 v41, v14, v41
	v_mad_i64_i32 v[60:61], s[0:1], v41, s56, v[16:17]
	v_add_u32_e32 v41, 6, v37
	global_load_dwordx2 v[62:63], v[60:61], off
	v_cndmask_b32_e64 v60, 0, 1.0, vcc
	v_cmp_lt_u32_e32 vcc, v41, v15
	s_and_b64 vcc, s[14:15], vcc
	v_lshlrev_b32_e32 v8, 16, v9
	v_cndmask_b32_e32 v41, v37, v41, vcc
	v_sub_u32_e32 v41, v41, v37
	v_add_u32_e32 v41, v14, v41
	v_mad_i64_i32 v[64:65], s[0:1], v41, s56, v[16:17]
	v_add_u32_e32 v41, 7, v37
	global_load_dwordx2 v[66:67], v[64:65], off
	v_cndmask_b32_e64 v64, 0, 1.0, vcc
	v_cmp_lt_u32_e32 vcc, v41, v15
	s_and_b64 vcc, s[14:15], vcc
	v_min_u32_e32 v15, v33, v15
	v_cndmask_b32_e32 v41, v37, v41, vcc
	v_sub_u32_e32 v37, v41, v37
	v_add_u32_e32 v37, v14, v37
	v_mad_i64_i32 v[68:69], s[0:1], v37, s56, v[16:17]
	global_load_dwordx2 v[70:71], v[68:69], off
	v_sub_u32_e32 v15, v15, v19
	v_cvt_f32_i32_e32 v15, v15
	v_cndmask_b32_e64 v68, 0, 1.0, vcc
	v_and_b32_e32 v9, 0xffff0000, v9
	v_lshlrev_b32_e32 v38, 16, v12
	v_div_scale_f32 v19, s[0:1], v15, v15, 1.0
	v_rcp_f32_e32 v33, v19
	v_and_b32_e32 v39, 0xffff0000, v12
	v_lshlrev_b32_e32 v12, 16, v13
	v_and_b32_e32 v13, 0xffff0000, v13
	v_fma_f32 v37, -v19, v33, 1.0
	v_fmac_f32_e32 v33, v37, v33
	v_div_scale_f32 v37, vcc, 1.0, v15, 1.0
	v_mul_f32_e32 v41, v37, v33
	v_fma_f32 v45, -v19, v41, v37
	v_pk_fma_f32 v[4:5], v[6:7], v[34:35], v[4:5] op_sel_hi:[0,1,1]
	v_pk_fma_f32 v[2:3], v[6:7], v[8:9], v[2:3] op_sel_hi:[0,1,1]
	v_lshlrev_b32_e32 v48, 16, v42
	v_and_b32_e32 v49, 0xffff0000, v42
	v_lshlrev_b32_e32 v42, 16, v43
	v_and_b32_e32 v43, 0xffff0000, v43
	v_fmac_f32_e32 v41, v45, v33
	v_pk_fma_f32 v[4:5], v[36:37], v[38:39], v[4:5] op_sel_hi:[0,1,1]
	v_pk_fma_f32 v[2:3], v[36:37], v[12:13], v[2:3] op_sel_hi:[0,1,1]
	v_lshlrev_b32_e32 v58, 16, v46
	v_and_b32_e32 v59, 0xffff0000, v46
	v_lshlrev_b32_e32 v46, 16, v47
	v_and_b32_e32 v47, 0xffff0000, v47
	v_pk_fma_f32 v[4:5], v[40:41], v[48:49], v[4:5] op_sel_hi:[0,1,1]
	v_pk_fma_f32 v[2:3], v[40:41], v[42:43], v[2:3] op_sel_hi:[0,1,1]
	v_pk_fma_f32 v[4:5], v[44:45], v[58:59], v[4:5] op_sel_hi:[0,1,1]
	v_lshlrev_b32_e32 v34, 16, v52
	v_and_b32_e32 v35, 0xffff0000, v52
	v_pk_fma_f32 v[2:3], v[44:45], v[46:47], v[2:3] op_sel_hi:[0,1,1]
	v_lshlrev_b32_e32 v8, 16, v53
	v_and_b32_e32 v9, 0xffff0000, v53
	v_pk_fma_f32 v[4:5], v[50:51], v[34:35], v[4:5] op_sel_hi:[0,1,1]
	v_pk_fma_f32 v[2:3], v[50:51], v[8:9], v[2:3] op_sel_hi:[0,1,1]
	v_fma_f32 v19, -v19, v41, v37
	v_div_fmas_f32 v19, v19, v33, v41
	v_div_fixup_f32 v72, v19, v15, 1.0
	v_mov_b32_e32 v15, v220
	v_mov_b32_e32 v19, v220
	v_mov_b32_e32 v33, v220
	s_waitcnt vmcnt(0)
	v_lshlrev_b32_e32 v34, 16, v56
	v_and_b32_e32 v35, 0xffff0000, v56
	v_lshlrev_b32_e32 v8, 16, v57
	v_and_b32_e32 v9, 0xffff0000, v57
	v_pk_fma_f32 v[4:5], v[54:55], v[34:35], v[4:5] op_sel_hi:[0,1,1]
	v_pk_fma_f32 v[2:3], v[54:55], v[8:9], v[2:3] op_sel_hi:[0,1,1]
	v_lshlrev_b32_e32 v34, 16, v62
	v_and_b32_e32 v35, 0xffff0000, v62
	v_lshlrev_b32_e32 v8, 16, v63
	v_and_b32_e32 v9, 0xffff0000, v63
	v_pk_fma_f32 v[4:5], v[60:61], v[34:35], v[4:5] op_sel_hi:[0,1,1]
	v_pk_fma_f32 v[2:3], v[60:61], v[8:9], v[2:3] op_sel_hi:[0,1,1]
	v_lshlrev_b32_e32 v34, 16, v66
	v_and_b32_e32 v35, 0xffff0000, v66
	v_lshlrev_b32_e32 v8, 16, v67
	v_and_b32_e32 v9, 0xffff0000, v67
	v_pk_fma_f32 v[4:5], v[64:65], v[34:35], v[4:5] op_sel_hi:[0,1,1]
	v_pk_fma_f32 v[2:3], v[64:65], v[8:9], v[2:3] op_sel_hi:[0,1,1]
	v_lshlrev_b32_e32 v34, 16, v70
	v_and_b32_e32 v35, 0xffff0000, v70
	v_lshlrev_b32_e32 v8, 16, v71
	v_and_b32_e32 v9, 0xffff0000, v71
	v_pk_fma_f32 v[4:5], v[68:69], v[34:35], v[4:5] op_sel_hi:[0,1,1]
	v_pk_fma_f32 v[2:3], v[68:69], v[8:9], v[2:3] op_sel_hi:[0,1,1]
	v_pk_fma_f32 v[4:5], v[72:73], v[4:5], v[38:39] op_sel_hi:[0,1,1] neg_lo:[0,0,1] neg_hi:[0,0,1]
	v_pk_fma_f32 v[2:3], v[72:73], v[2:3], v[12:13] op_sel_hi:[0,1,1] neg_lo:[0,0,1] neg_hi:[0,0,1]
	v_cvt_pk_bf16_f32 v4, v4, v5
	v_cvt_pk_bf16_f32 v5, v2, v3
	v_lshl_add_u64 v[2:3], s[2:3], 0, v[22:23]
	global_store_dwordx2 v[2:3], v[4:5], off
	v_mov_b32_e32 v2, v82
	v_mov_b32_e32 v3, v83
	v_mov_b32_e32 v6, v86
	v_mov_b32_e32 v9, v220
	v_mov_b32_e32 v10, v220
	v_mov_b32_e32 v11, v220
	v_mov_b32_e32 v12, v220
	v_mov_b32_e32 v13, v220
	v_mov_b32_e32 v34, v220
	v_lshlrev_b32_e32 v5, 16, v3
	v_lshlrev_b32_e32 v4, 16, v2
	v_and_b32_e32 v8, 0xffff0000, v2
	v_pk_mul_f32 v[4:5], v[4:5], v[4:5]
	s_nop 0
	v_fma_f32 v2, v8, v8, v4
	v_add_f32_e32 v2, v5, v2
	v_and_b32_e32 v4, 0xffff0000, v3
	v_lshlrev_b32_e32 v5, 16, v6
	v_and_b32_e32 v3, 0xffff0000, v6
	v_mov_b32_e32 v6, v220
	v_mov_b32_e32 v8, v220
	v_mul_f32_e32 v3, v3, v3
	v_lshlrev_b32_e32 v6, 2, v6
	v_lshlrev_b32_e32 v13, 2, v13
	v_xor_b32_e32 v6, 0x80, v6
	v_xor_b32_e32 v13, 0x80, v13
	v_pk_fma_f32 v[2:3], v[4:5], v[4:5], v[2:3]
	ds_bpermute_b32 v4, v6, v2
	ds_bpermute_b32 v5, v13, v3
	v_lshlrev_b32_e32 v8, 2, v8
	v_lshlrev_b32_e32 v15, 2, v15
	v_xor_b32_e32 v8, 64, v8
	v_xor_b32_e32 v15, 64, v15
	s_waitcnt lgkmcnt(0)
	v_pk_add_f32 v[2:3], v[2:3], v[4:5]
	ds_bpermute_b32 v4, v8, v2
	ds_bpermute_b32 v5, v15, v3
	v_lshlrev_b32_e32 v9, 2, v9
	v_lshlrev_b32_e32 v19, 2, v19
	v_xor_b32_e32 v9, 32, v9
	v_xor_b32_e32 v19, 32, v19
	s_waitcnt lgkmcnt(0)
	v_pk_add_f32 v[2:3], v[2:3], v[4:5]
	ds_bpermute_b32 v4, v9, v2
	ds_bpermute_b32 v5, v19, v3
	v_lshlrev_b32_e32 v10, 2, v10
	v_lshlrev_b32_e32 v33, 2, v33
	v_xor_b32_e32 v10, 16, v10
	v_xor_b32_e32 v33, 16, v33
	s_waitcnt lgkmcnt(0)
	v_pk_add_f32 v[2:3], v[2:3], v[4:5]
	ds_bpermute_b32 v4, v10, v2
	ds_bpermute_b32 v5, v33, v3
	v_lshlrev_b32_e32 v11, 2, v11
	v_lshlrev_b32_e32 v34, 2, v34
	v_xor_b32_e32 v11, 8, v11
	v_xor_b32_e32 v34, 8, v34
	s_waitcnt lgkmcnt(0)
	v_pk_add_f32 v[2:3], v[2:3], v[4:5]
	ds_bpermute_b32 v4, v11, v2
	ds_bpermute_b32 v5, v34, v3
	v_lshlrev_b32_e32 v12, 2, v12
	v_xor_b32_e32 v12, 4, v12
	s_waitcnt lgkmcnt(0)
	v_pk_add_f32 v[2:3], v[2:3], v[4:5]
	v_mov_b32_e32 v5, v220
	ds_bpermute_b32 v4, v12, v2
	v_lshlrev_b32_e32 v5, 2, v5
	v_xor_b32_e32 v5, 4, v5
	ds_bpermute_b32 v5, v5, v3
	s_and_saveexec_b64 s[0:1], s[4:5]
	s_cbranch_execz .LBB0_491
; __device__ __forceinline__ float bf_lo(unsigned u) { return __uint_as_float(u << 16); }
; __device__ __forceinline__ float bf_hi(unsigned u) { return __uint_as_float(u & 0xffff0000u); }
; __device__ void prep_phase(PK p) {
;     ...
;             sq = wave_sum(sq); sk = wave_sum(sk);
;             if (lane == 0) { RSTD[row * 2] = rsqrtf(sq * (1.0f / 256.0f) + NEPS); RSTD[row * 2 + 1] = rsqrtf(sk * (1.0f / 128.0f) + NEPS); }
;         }
;         if (lane < 34) {
;             const bool iskr = lane >= 32; const int a = lane & 1;
;             bf16_t* ep = iskr ? prow + C_MKR + a * 16 : prow + ((lane >> 4) ? C_DK : C_DQ) + ((lane >> 1) & 7) * 32 + a * 16;
;             const u32x4 e0 = *(const u32x4*)ep, e1 = *(const u32x4*)(ep + 8);
;             float x1[8], x2[8];
;             x1[0] = bf_lo(e0.x); x1[1] = bf_hi(e0.x); x1[2] = bf_lo(e0.y); x1[3] = bf_hi(e0.y); x1[4] = bf_lo(e0.z); x1[5] = bf_hi(e0.z); x1[6] = bf_lo(e0.w); x1[7] = bf_hi(e0.w);
;             x2[0] = bf_lo(e1.x); x2[1] = bf_hi(e1.x); x2[2] = bf_lo(e1.y); x2[3] = bf_hi(e1.y); x2[4] = bf_lo(e1.z); x2[5] = bf_hi(e1.z); x2[6] = bf_lo(e1.w); x2[7] = bf_hi(e1.w);
;             if (lat) { const int pos = a ? (t & 63) : (t >> 6);
; #pragma unroll
;                 for (int i = 0; i < 8; ++i) { const float2 cs = RT[pos * 8 + i]; const float o1 = x1[i] * cs.x - x2[i] * cs.y, o2 = x1[i] * cs.y + x2[i] * cs.x; x1[i] = o1; x2[i] = o2; } }
	s_waitcnt lgkmcnt(0)
	v_pk_add_f32 v[2:3], v[2:3], v[4:5]
	s_mov_b32 s2, 0x45800000
	v_pk_fma_f32 v[2:3], v[2:3], s[86:87], v[188:189] op_sel_hi:[1,1,0]
	v_ashrrev_i32_e32 v19, 31, v18
	v_mul_f32_e32 v4, 0x4b800000, v2
	v_cmp_gt_f32_e64 s[20:21], s44, v2
	v_cmp_gt_f32_e32 vcc, s44, v3
	v_lshl_add_u64 v[8:9], v[18:19], 2, s[24:25]
	v_cndmask_b32_e64 v2, v2, v4, s[20:21]
	v_mul_f32_e32 v4, 0x4b800000, v3
	v_cndmask_b32_e32 v3, v3, v4, vcc
	v_rsq_f32_e32 v2, v2
	v_rsq_f32_e32 v3, v3
	s_nop 0
	v_pk_mul_f32 v[4:5], v[2:3], s[2:3] op_sel_hi:[1,0]
	s_nop 0
	v_cndmask_b32_e32 v3, v3, v5, vcc
	v_cndmask_b32_e64 v2, v2, v4, s[20:21]
	global_store_dwordx2 v[8:9], v[2:3], off
.LBB0_491:
	s_or_b64 exec, exec, s[0:1]
	s_and_saveexec_b64 s[2:3], s[6:7]
	s_cbranch_execz .LBB0_488
	v_readlane_b32 s0, v254, 56
	v_readlane_b32 s1, v254, 57
	v_mov_b32_e32 v33, v0
	s_nop 0
	v_lshl_add_u64 v[2:3], s[0:1], 0, v[28:29]
	s_waitcnt lgkmcnt(0)
	v_lshl_add_u64 v[4:5], s[0:1], 0, v[26:27]
	v_cndmask_b32_e64 v3, v5, v3, s[8:9]
	v_cndmask_b32_e64 v2, v4, v2, s[8:9]
	v_lshl_add_u64 v[34:35], v[2:3], 0, v[32:33]
	v_and_b32_e32 v39, 0xffff0000, v88
	v_lshlrev_b32_e32 v38, 16, v88
	v_and_b32_e32 v37, 0xffff0000, v92
	v_lshlrev_b32_e32 v36, 16, v92
	v_and_b32_e32 v43, 0xffff0000, v89
	v_lshlrev_b32_e32 v42, 16, v89
	v_and_b32_e32 v41, 0xffff0000, v93
	v_lshlrev_b32_e32 v40, 16, v93
	v_and_b32_e32 v47, 0xffff0000, v90
	v_lshlrev_b32_e32 v46, 16, v90
	v_and_b32_e32 v45, 0xffff0000, v94
	v_lshlrev_b32_e32 v44, 16, v94
	v_and_b32_e32 v51, 0xffff0000, v91
	v_lshlrev_b32_e32 v50, 16, v91
	v_and_b32_e32 v49, 0xffff0000, v95
	v_lshlrev_b32_e32 v48, 16, v95
	s_and_saveexec_b64 s[20:21], s[18:19]
	s_cbranch_execz .LBB0_494
	v_and_b32_e32 v2, 63, v14
	v_lshrrev_b32_e32 v3, 6, v7
	v_cndmask_b32_e64 v2, v2, v3, s[12:13]
	v_lshlrev_b32_e32 v15, 6, v2
	v_mov_b64_e32 v[6:7], v[108:109]
	v_mov_b64_e32 v[8:9], v[110:111]
	v_mov_b64_e32 v[2:3], v[104:105]
	v_mov_b64_e32 v[4:5], v[106:107]
	v_mov_b64_e32 v[10:11], v[100:101]
	v_mov_b64_e32 v[12:13], v[102:103]
	v_mov_b64_e32 v[52:53], v[96:97]
	v_mov_b64_e32 v[54:55], v[98:99]
	v_mov_b32_e32 v60, v7
	v_mov_b32_e32 v61, v9
	v_pk_mul_f32 v[60:61], v[60:61], v[50:51]
	v_mov_b32_e32 v56, v53
	v_mov_b32_e32 v57, v55
	v_pk_mul_f32 v[58:59], v[56:57], v[38:39]
	v_mov_b32_e32 v53, v54
	v_pk_mul_f32 v[54:55], v[56:57], v[36:37]
	v_mov_b32_e32 v56, v11
	v_mov_b32_e32 v57, v13
	v_pk_fma_f32 v[36:37], v[52:53], v[36:37], v[58:59]
	v_pk_mul_f32 v[58:59], v[56:57], v[42:43]
	v_mov_b32_e32 v11, v12
	v_pk_mul_f32 v[12:13], v[56:57], v[40:41]
	v_mov_b32_e32 v56, v3
	v_mov_b32_e32 v57, v5
	v_pk_fma_f32 v[40:41], v[10:11], v[40:41], v[58:59]
	v_pk_mul_f32 v[58:59], v[56:57], v[46:47]
	v_mov_b32_e32 v3, v4
	v_pk_mul_f32 v[4:5], v[56:57], v[44:45]
	v_mul_f32_e32 v56, v6, v50
	v_mov_b32_e32 v50, v51
	v_mov_b32_e32 v51, v49
	v_pk_fma_f32 v[44:45], v[2:3], v[44:45], v[58:59]
	v_mul_f32_e32 v58, v7, v48
	v_mov_b32_e32 v7, v8
	v_pk_mul_f32 v[8:9], v[8:9], v[50:51]
	v_pk_fma_f32 v[48:49], v[6:7], v[48:49], v[60:61]
	v_mov_b32_e32 v57, v8
	v_mov_b32_e32 v59, v9
	v_pk_fma_f32 v[38:39], v[52:53], v[38:39], v[54:55] neg_lo:[0,0,1] neg_hi:[0,0,1]
	v_pk_fma_f32 v[42:43], v[10:11], v[42:43], v[12:13] neg_lo:[0,0,1] neg_hi:[0,0,1]
	v_pk_fma_f32 v[46:47], v[2:3], v[46:47], v[4:5] neg_lo:[0,0,1] neg_hi:[0,0,1]
	v_pk_add_f32 v[50:51], v[56:57], v[58:59] neg_lo:[0,1] neg_hi:[0,1]
